# v18 plus layer-0 dense attention loop: 4-slot V ring, mid-tile barrier removed (one barrier per key tile)
# speedup vs baseline: 1.0070x; 1.0009x over previous
; __device__ __forceinline__ int v_st_ns(int k, int c) { return ((k >> 3) * 2 + (c >> 5)) * 512 + ((k & 7) * 32 + (c & 31)) * 2; }
; __device__ __forceinline__ int v_rd_base(int lane) { return ((lane & 3) << 3) | (((lane >> 2) & 3) << 6) | (((lane >> 4) & 1) << 5) | (((lane >> 5) & 1) << 8); }
; #define SLOAD(i, k0) do { st_[i].vs = *reinterpret_cast<const bf16x8*>(&Vh[(size_t)((k0) + sr) * LDK + sc]); \
;     st_[i].ks = *reinterpret_cast<const bf16x8*>(&Kh[(size_t)((k0) + sr) * LDK + sc]); \
;     if (DQ == 96) st_[i].kr = *reinterpret_cast<const bf16x8*>(&Kr[(size_t)((k0) + sr2) * 32 + sc2]); } while (0)
; template <int DQ, bool WIN, int LDQ, int LDK> ...
;     ...
;     const bf16_t* Qw = Qb + (size_t)(wid * 32 + r32) * LDQ + hi * 8;
; #pragma unroll
;     for (int d0 = 0; d0 < ND; ++d0) qr[d0] = *reinterpret_cast<const bf16x8*>(Qw + d0 * 16);
;     const int sr = tid >> 3, sc = (tid & 7) * 8, vst0 = v_st_ns(sr, sc);
;     const int kst0 = sr * KROW + sc * 2;
;     const int sr2 = (tid & 255) >> 2, sc2 = (tid & 3) * 8; const int kst2 = sr2 * KROW + 128 + sc2 * 2;
;     const int vb0 = (int)(uintptr_t)V_lds + v_rd_base(lane);
;     const int qrow = q0 + wid * 32 + r32;
;     struct { bf16x8 vs, ks, kr; } st_[2];
;     ...
;     f32x16 pA0, pA1, pB0, pB1; bf16x8 pa0, pa1, pa2, pa3;
;     auto finish = [&](f32x16& p0, f32x16& p1) {
;         exp16(p1);
;         pack_p_ns(p0, p1, pa0, pa1, pa2, pa3);
;     };
;     auto pv = [&](int vb) {
;         pv_d0(o, vb, pa0, pa1, pa2, pa3);
;     };
;     auto lsum_upd = [&]() {
;         lsum = __builtin_amdgcn_mfma_f32_32x32x16_bf16(pa0, ones8, lsum, 0, 0, 0);
;         lsum = __builtin_amdgcn_mfma_f32_32x32x16_bf16(pa1, ones8, lsum, 0, 0, 0);
;         lsum = __builtin_amdgcn_mfma_f32_32x32x16_bf16(pa2, ones8, lsum, 0, 0, 0);
;         lsum = __builtin_amdgcn_mfma_f32_32x32x16_bf16(pa3, ones8, lsum, 0, 0, 0);
;     };
;     constexpr int SE = 0, SO = 1;
;     SLOAD(SE, KBASE(0)); SLOAD(SO, KBASE(1));
;     SWAIT(); SWRITE(0, SE); __syncthreads();
;     qkt<DQ>(pA0, pA1, K_lds, qr, zero16, r32, hi);
;     if (WIN) win_mask(pA0, pA1, qrow - KBASE(0), hi);
;     { const float pm = row_max32(pA0, pA1); m_ref = (pm > -1e37f) ? pm : 0.f;
; #pragma unroll
;       for (int r = 0; r < 16; ++r) { minit[r] = -m_ref; pA0[r] -= m_ref; pA1[r] -= m_ref; } }
;     exp16(pA0);
.LBB0_491:
	s_or_b64 exec, exec, s[0:1]
	s_or_b32 s10, s65, s63
	s_mul_i32 s0, s10, 0xc00
	s_add_u32 s0, s69, s0
	s_addc_u32 s1, s70, 0
	s_lshl_b32 s11, s64, 6
	s_lshl_b32 s4, s64, 7
	s_add_u32 s6, s0, s4
	s_addc_u32 s7, s1, 0
	s_add_u32 s0, s69, s62
	s_addc_u32 s1, s70, 0
	s_lshl_b32 s4, s37, 7
	s_add_u32 s4, s0, s4
	v_ashrrev_i32_e32 v35, 3, v34
	v_lshlrev_b32_e32 v12, 3, v34
	s_addc_u32 s5, s1, 0
	v_and_b32_e32 v82, 56, v12
	v_mad_i64_i32 v[2:3], s[0:1], v35, s83, 0
	v_or_b32_e32 v2, v2, v82
	v_lshl_add_u64 v[6:7], v[2:3], 1, s[4:5]
	global_load_dwordx4 v[2:5], v[6:7], off offset:1280
	s_nop 0
	global_load_dwordx4 v[6:9], v[6:7], off offset:1024
	s_ashr_i32 s20, s20, 1
	v_mov_b32_e32 v10, s20
	v_bfe_u32 v1, v34, 5, 1
	v_bfi_b32 v13, s79, v10, v34
	v_mov_b64_e32 v[10:11], s[6:7]
	v_mad_i64_i32 v[10:11], s[0:1], v13, s78, v[10:11]
	v_lshlrev_b32_e32 v146, 4, v1
	v_lshl_add_u64 v[10:11], v[10:11], 0, v[146:147]
	global_load_dwordx4 v[126:129], v[10:11], off
	global_load_dwordx4 v[122:125], v[10:11], off offset:32
	global_load_dwordx4 v[118:121], v[10:11], off offset:64
	global_load_dwordx4 v[114:117], v[10:11], off offset:96
	v_bfe_u32 v14, v12, 5, 1
	v_lshlrev_b32_e32 v15, 5, v35
	v_and_b32_e32 v12, 24, v12
	v_lshrrev_b32_e32 v13, 5, v34
	v_add_u32_e32 v17, 64, v35
	v_and_or_b32 v12, v15, s81, v12
	v_and_b32_e32 v150, 31, v34
	v_and_or_b32 v13, v13, s80, v14
	v_mad_i64_i32 v[10:11], s[0:1], v17, s83, 0
	v_lshlrev_b32_e32 v12, 1, v12
	v_mul_lo_u32 v16, v35, s82
	s_waitcnt vmcnt(0)
	v_mad_u32_u24 v18, v150, s82, 0
	v_or_b32_e32 v10, v10, v82
	v_lshl_or_b32 v12, v13, 9, v12
	v_lshl_add_u32 v14, v82, 1, v16
	v_add_u32_e32 v156, v18, v146
	v_add_u32_e32 v158, 0, v12
	v_lshl_add_u64 v[10:11], v[10:11], 1, s[4:5]
	v_add_u32_e32 v157, 0, v14
	global_load_dwordx4 v[36:39], v[10:11], off offset:1280
	global_load_dwordx4 v[40:43], v[10:11], off offset:1024
	s_waitcnt vmcnt(2)
	v_and_b32_e32 v151, 63, v34
	s_andn2_b32 s20, s20, 31
	s_cmp_lg_u32 0, -1
	s_cselect_b32 s22, 0, 0
	s_mov_b32 s21, -1
	ds_write_b128 v158, v[2:5]
	ds_write_b128 v157, v[6:9] offset:16384
	s_waitcnt lgkmcnt(0)
	s_barrier
	ds_read_b128 v[2:5], v156 offset:16384
	ds_read_b128 v[44:47], v156 offset:16416
	s_waitcnt lgkmcnt(1)
	v_mfma_f32_32x32x16_bf16 v[18:33], v[2:5], v[126:129], 0
	ds_read_b128 v[2:5], v156 offset:20992
	ds_read_b128 v[48:51], v156 offset:21024
	s_waitcnt lgkmcnt(1)
	v_mfma_f32_32x32x16_bf16 v[2:17], v[2:5], v[126:129], 0
	v_mfma_f32_32x32x16_bf16 v[18:33], v[44:47], v[122:125], v[18:33]
	s_waitcnt lgkmcnt(0)
	v_mfma_f32_32x32x16_bf16 v[2:17], v[48:51], v[122:125], v[2:17]
	ds_read_b128 v[44:47], v156 offset:16448
	ds_read_b128 v[48:51], v156 offset:16480
	s_waitcnt lgkmcnt(1)
	v_mfma_f32_32x32x16_bf16 v[18:33], v[44:47], v[118:121], v[18:33]
	ds_read_b128 v[44:47], v156 offset:21056
	ds_read_b128 v[52:55], v156 offset:21088
	s_waitcnt lgkmcnt(2)
	v_mfma_f32_32x32x16_bf16 v[18:33], v[48:51], v[114:117], v[18:33]
	s_waitcnt lgkmcnt(1)
	v_mfma_f32_32x32x16_bf16 v[2:17], v[44:47], v[118:121], v[2:17]
	v_lshlrev_b32_e32 v44, 4, v34
	v_lshlrev_b32_e32 v45, 1, v34
	v_lshlrev_b32_e32 v46, 3, v151
	v_and_b32_e32 v44, 0xc0, v44
	v_and_b32_e32 v45, 32, v45
	v_and_or_b32 v44, v46, 24, v44
	v_and_b32_e32 v46, 0x100, v46
	v_or3_b32 v44, v44, v45, v46
	s_nop 1
	v_max_f32_e32 v45, v19, v19
	v_max_f32_e32 v46, v18, v18
	s_waitcnt lgkmcnt(0)
	v_mfma_f32_32x32x16_bf16 v[2:17], v[52:55], v[114:117], v[2:17]
	v_max_f32_e32 v45, v46, v45
	v_max3_f32 v45, v45, v20, v21
	v_max3_f32 v45, v45, v22, v23
	v_max3_f32 v45, v45, v24, v25
	v_max3_f32 v45, v45, v26, v27
	v_max3_f32 v45, v45, v28, v29
	v_max3_f32 v45, v45, v30, v31
	v_max3_f32 v45, v45, v32, v33
	s_nop 3
	v_max3_f32 v45, v45, v2, v3
	v_max3_f32 v45, v45, v4, v5
	v_max3_f32 v45, v45, v6, v7
	v_max3_f32 v45, v45, v8, v9
	v_max3_f32 v45, v45, v10, v11
	v_max3_f32 v45, v45, v12, v13
	v_max3_f32 v45, v45, v14, v15
	v_max3_f32 v45, v45, v16, v17
	v_mov_b32_e32 v46, v45
	s_nop 1
	v_permlane32_swap_b32_e32 v45, v46
	v_max_f32_e32 v46, v46, v46
	v_max_f32_e32 v45, v45, v45
	v_max_f32_e32 v45, v45, v46
	v_cmp_lt_f32_e32 vcc, s85, v45
	v_add_u32_e32 v159, s22, v44
	s_addk_i32 s22, 0x2000
	v_cndmask_b32_e32 v45, 0, v45, vcc
	v_sub_f32_e32 v66, v2, v45
	v_add_u32_e32 v2, 0x80, v35
	v_sub_f32_e32 v67, v3, v45
	v_mad_i64_i32 v[2:3], s[0:1], v2, s83, 0
	v_or_b32_e32 v2, v2, v82
	v_lshl_add_u64 v[2:3], v[2:3], 1, s[4:5]
	global_load_dwordx4 v[130:133], v[2:3], off offset:1024
	global_load_dwordx4 v[134:137], v[2:3], off offset:1280
	s_add_u32 s0, s33, s67
	s_addc_u32 s1, 0, 0
	v_sub_f32_e32 v18, v18, v45
	v_sub_f32_e32 v19, v19, v45
	v_sub_f32_e32 v20, v20, v45
	v_sub_f32_e32 v21, v21, v45
	v_sub_f32_e32 v22, v22, v45
	v_sub_f32_e32 v23, v23, v45
	v_sub_f32_e32 v24, v24, v45
	v_sub_f32_e32 v25, v25, v45
	v_sub_f32_e32 v26, v26, v45
	v_sub_f32_e32 v27, v27, v45
	v_sub_f32_e32 v28, v28, v45
	v_sub_f32_e32 v29, v29, v45
	v_sub_f32_e32 v30, v30, v45
	v_sub_f32_e32 v31, v31, v45
	v_sub_f32_e32 v32, v32, v45
	v_sub_f32_e32 v33, v33, v45
	v_sub_f32_e32 v68, v4, v45
	v_mov_b64_e32 v[2:3], s[0:1]
	v_and_b32_e32 v4, 7, v34
	v_exp_f32_e32 v138, v18
	v_exp_f32_e32 v139, v19
	v_exp_f32_e32 v162, v20
	v_exp_f32_e32 v165, v21
	v_exp_f32_e32 v163, v22
	v_exp_f32_e32 v166, v23
	v_exp_f32_e32 v164, v24
	v_exp_f32_e32 v167, v25
	v_exp_f32_e32 v140, v26
	v_exp_f32_e32 v144, v27
	v_exp_f32_e32 v141, v28
	v_exp_f32_e32 v145, v29
	v_exp_f32_e32 v142, v30
	v_exp_f32_e32 v160, v31
	v_exp_f32_e32 v143, v32
	v_exp_f32_e32 v161, v33
	v_mad_i64_i32 v[2:3], s[0:1], v35, s78, v[2:3]
	v_lshlrev_b32_e32 v146, 4, v4
	s_waitcnt vmcnt(2)
; #define SLOAD(i, k0) do { st_[i].vs = *reinterpret_cast<const bf16x8*>(&Vh[(size_t)((k0) + sr) * LDK + sc]); \
;     st_[i].ks = *reinterpret_cast<const bf16x8*>(&Kh[(size_t)((k0) + sr) * LDK + sc]); \
;     if (DQ == 96) st_[i].kr = *reinterpret_cast<const bf16x8*>(&Kr[(size_t)((k0) + sr2) * 32 + sc2]); } while (0)
; #define SWRITE(b, i) do { *(bf16x8*)(V_lds + (b) * SHM_V + vst0) = st_[i].vs; *(bf16x8*)(K_lds + (b) * SHM_K + kst0) = st_[i].ks; \
;     if (DQ == 96) { if (tid < 256) *(bf16x8*)(K_lds + (b) * SHM_K + kst2) = st_[i].kr; } } while (0)
; #define SWAIT() do { if (DQ == 96) asm volatile("s_waitcnt vmcnt(3)" ::: "memory"); else asm volatile("s_waitcnt vmcnt(2)" ::: "memory"); } while (0)
; #define SLOAD(i, k0) do { st_[i].vs = *reinterpret_cast<const bf16x8*>(&Vh[(size_t)((k0) + sr) * LDK + sc]); \
;     st_[i].ks = *reinterpret_cast<const bf16x8*>(&Kh[(size_t)((k0) + sr) * LDK + sc]); \
;     if (DQ == 96) st_[i].kr = *reinterpret_cast<const bf16x8*>(&Kr[(size_t)((k0) + sr2) * 32 + sc2]); } while (0)
; #define SWRITE(b, i) do { *(bf16x8*)(V_lds + (b) * SHM_V + vst0) = st_[i].vs; *(bf16x8*)(K_lds + (b) * SHM_K + kst0) = st_[i].ks; \
;     if (DQ == 96) { if (tid < 256) *(bf16x8*)(K_lds + (b) * SHM_K + kst2) = st_[i].kr; } } while (0)
; #define SWAIT() do { if (DQ == 96) asm volatile("s_waitcnt vmcnt(3)" ::: "memory"); else asm volatile("s_waitcnt vmcnt(2)" ::: "memory"); } while (0)
; template <int DQ, bool WIN, int LDQ, int LDK> ...
;     ...
;     { const float pm = row_max32(pA0, pA1); m_ref = (pm > -1e37f) ? pm : 0.f;
; #pragma unroll
;       for (int r = 0; r < 16; ++r) { minit[r] = -m_ref; pA0[r] -= m_ref; pA1[r] -= m_ref; } }
;     exp16(pA0);
;     if (2 < NT) SLOAD(SE, KBASE(2));
;     SWAIT(); SWRITE(1, SO); __syncthreads();
;     ...
;         pv(vb0 + SHM_V);
;         __syncthreads(); SWAIT(); SWRITE(1, SO);
;         lsum_upd();
;         if (WIN) win_mask(pA0, pA1, qrow - KBASE(j + 1), hi);
;         exp16(pA0);
;         __syncthreads();
	v_lshl_add_u64 v[2:3], v[2:3], 0, v[146:147]
	v_xor_b32_e32 v50, 0x80000000, v45
	v_lshl_add_u64 v[148:149], s[16:17], 0, v[2:3]
	v_mov_b32_e32 v2, 0
	v_sub_f32_e32 v81, v17, v45
	v_sub_f32_e32 v80, v16, v45
	v_sub_f32_e32 v79, v15, v45
	v_sub_f32_e32 v78, v14, v45
	v_sub_f32_e32 v77, v13, v45
	v_sub_f32_e32 v76, v12, v45
	v_sub_f32_e32 v75, v11, v45
	v_sub_f32_e32 v74, v10, v45
	v_sub_f32_e32 v73, v9, v45
	v_mov_b32_e32 v51, v50
	v_mov_b32_e32 v52, v50
	v_mov_b32_e32 v53, v50
	v_mov_b32_e32 v54, v50
	v_mov_b32_e32 v55, v50
	v_mov_b32_e32 v56, v50
	v_mov_b32_e32 v57, v50
	v_mov_b32_e32 v58, v50
	v_mov_b32_e32 v59, v50
	v_mov_b32_e32 v60, v50
	v_mov_b32_e32 v61, v50
	v_mov_b32_e32 v62, v50
	v_mov_b32_e32 v63, v50
	v_mov_b32_e32 v64, v50
	v_mov_b32_e32 v65, v50
	v_sub_f32_e32 v72, v8, v45
	v_sub_f32_e32 v71, v7, v45
	v_sub_f32_e32 v70, v6, v45
	v_sub_f32_e32 v69, v5, v45
	s_waitcnt vmcnt(3)
	ds_write_b128 v158, v[36:39] offset:8192
	s_waitcnt vmcnt(2)
	ds_write_b128 v157, v[40:43] offset:25600
	v_add_u32_e32 v155, s22, v44
	v_mov_b32_e32 v3, v2
	v_mov_b32_e32 v4, v2
	v_mov_b32_e32 v5, v2
	v_mov_b32_e32 v6, v2
	v_mov_b32_e32 v7, v2
	v_mov_b32_e32 v8, v2
	v_mov_b32_e32 v9, v2
	v_mov_b32_e32 v10, v2
	v_mov_b32_e32 v11, v2
	v_mov_b32_e32 v12, v2
	v_mov_b32_e32 v13, v2
	v_mov_b32_e32 v14, v2
	v_mov_b32_e32 v15, v2
	v_mov_b32_e32 v16, v2
	v_mov_b32_e32 v17, v2
	v_mov_b32_e32 v18, v2
	v_mov_b32_e32 v19, v2
	v_mov_b32_e32 v20, v2
	v_mov_b32_e32 v21, v2
	v_mov_b32_e32 v22, v2
	v_mov_b32_e32 v23, v2
	v_mov_b32_e32 v24, v2
	v_mov_b32_e32 v25, v2
	v_mov_b32_e32 v26, v2
	v_mov_b32_e32 v27, v2
	v_mov_b32_e32 v28, v2
	v_mov_b32_e32 v29, v2
	v_mov_b32_e32 v30, v2
	v_mov_b32_e32 v31, v2
	v_mov_b32_e32 v32, v2
	v_mov_b32_e32 v33, v2
	v_mov_b32_e32 v34, v2
	v_mov_b32_e32 v35, v2
	v_mov_b32_e32 v36, v2
	v_mov_b32_e32 v37, v2
	v_mov_b32_e32 v38, v2
	v_mov_b32_e32 v39, v2
	v_mov_b32_e32 v40, v2
	v_mov_b32_e32 v41, v2
	v_mov_b32_e32 v42, v2
	v_mov_b32_e32 v43, v2
	v_mov_b32_e32 v44, v2
	v_mov_b32_e32 v45, v2
	v_mov_b32_e32 v46, v2
	v_mov_b32_e32 v47, v2
	v_mov_b32_e32 v48, v2
	v_mov_b32_e32 v49, v2
	v_xor_b32_e32 v158, 0xc000, v158
	s_waitcnt lgkmcnt(0)
	s_barrier
	s_branch .LBB0_493
.LBB0_492:
	ds_read_b64_tr_b16 v[160:161], v155 offset:0
	ds_read_b64_tr_b16 v[162:163], v155 offset:0x400
	ds_read_b64_tr_b16 v[164:165], v155 offset:0x800
	ds_read_b64_tr_b16 v[166:167], v155 offset:0xc00
	ds_read_b64_tr_b16 v[168:169], v155 offset:0x1000
	ds_read_b64_tr_b16 v[170:171], v155 offset:0x1400
	ds_read_b64_tr_b16 v[172:173], v155 offset:0x1800
	ds_read_b64_tr_b16 v[174:175], v155 offset:0x1c00
	s_waitcnt lgkmcnt(0)
	s_nop 0
	v_mfma_f32_32x32x16_bf16 v[2:17], v[94:97], v[160:163], v[2:17]
	ds_read_b64_tr_b16 v[160:161], v155 offset:0x200
	ds_read_b64_tr_b16 v[162:163], v155 offset:0x600
	v_mfma_f32_32x32x16_bf16 v[2:17], v[90:93], v[164:167], v[2:17]
	ds_read_b64_tr_b16 v[164:165], v155 offset:0xa00
	ds_read_b64_tr_b16 v[166:167], v155 offset:0xe00
	v_mfma_f32_32x32x16_bf16 v[2:17], v[86:89], v[168:171], v[2:17]
	ds_read_b64_tr_b16 v[168:169], v155 offset:0x1200
	ds_read_b64_tr_b16 v[170:171], v155 offset:0x1600
	ds_read_b64_tr_b16 v[176:177], v155 offset:0x1a00
	ds_read_b64_tr_b16 v[178:179], v155 offset:0x1e00
	s_waitcnt lgkmcnt(0)
	v_mfma_f32_32x32x16_bf16 v[2:17], v[82:85], v[172:175], v[2:17]
	v_mfma_f32_32x32x16_bf16 v[18:33], v[94:97], v[160:163], v[18:33]
	s_waitcnt vmcnt(2)
	s_waitcnt vmcnt(1)
	ds_write_b128 v158, v[138:141] offset:8192
	s_waitcnt vmcnt(0)
	ds_write_b128 v157, v[142:145] offset:25600
	v_exp_f32_e32 v138, v98
	v_exp_f32_e32 v139, v99
	v_mfma_f32_32x32x16_bf16 v[18:33], v[90:93], v[164:167], v[18:33]
	v_exp_f32_e32 v162, v100
	v_exp_f32_e32 v165, v101
	v_exp_f32_e32 v163, v102
	v_exp_f32_e32 v166, v103
	v_exp_f32_e32 v164, v104
	v_exp_f32_e32 v167, v105
	v_exp_f32_e32 v140, v106
	v_mfma_f32_32x32x16_bf16 v[18:33], v[86:89], v[168:171], v[18:33]
	v_mov_b64_e32 v[170:171], s[14:15]
	v_mov_b64_e32 v[168:169], s[12:13]
	v_exp_f32_e32 v144, v107
	v_exp_f32_e32 v141, v108
	v_exp_f32_e32 v145, v109
	v_exp_f32_e32 v142, v110
	v_exp_f32_e32 v160, v111
	v_mfma_f32_32x32x16_bf16 v[34:49], v[94:97], v[168:171], v[34:49]
	v_exp_f32_e32 v143, v112
	v_exp_f32_e32 v161, v113
	v_lshl_add_u64 v[148:149], v[148:149], 0, s[18:19]
	s_and_b64 vcc, exec, s[0:1]
	s_waitcnt lgkmcnt(0)
	s_barrier
	v_mfma_f32_32x32x16_bf16 v[34:49], v[90:93], v[168:171], v[34:49]
	v_mfma_f32_32x32x16_bf16 v[34:49], v[86:89], v[168:171], v[34:49]
	v_mfma_f32_32x32x16_bf16 v[18:33], v[82:85], v[176:179], v[18:33]
	v_mfma_f32_32x32x16_bf16 v[34:49], v[82:85], v[168:171], v[34:49]
	v_xor_b32_e32 v158, 0xc000, v158
	v_xor_b32_e32 v159, 0xc000, v159
	v_xor_b32_e32 v155, 0xc000, v155
	s_cbranch_vccnz .LBB0_495
; #define SBAR() __builtin_amdgcn_sched_barrier(0)
; #define SLOAD(i, k0) do { st_[i].vs = *reinterpret_cast<const bf16x8*>(&Vh[(size_t)((k0) + sr) * LDK + sc]); \
;     st_[i].ks = *reinterpret_cast<const bf16x8*>(&Kh[(size_t)((k0) + sr) * LDK + sc]); \
;     if (DQ == 96) st_[i].kr = *reinterpret_cast<const bf16x8*>(&Kr[(size_t)((k0) + sr2) * 32 + sc2]); } while (0)
; #define SWRITE(b, i) do { *(bf16x8*)(V_lds + (b) * SHM_V + vst0) = st_[i].vs; *(bf16x8*)(K_lds + (b) * SHM_K + kst0) = st_[i].ks; \
;     if (DQ == 96) { if (tid < 256) *(bf16x8*)(K_lds + (b) * SHM_K + kst2) = st_[i].kr; } } while (0)
; #define SWAIT() do { if (DQ == 96) asm volatile("s_waitcnt vmcnt(3)" ::: "memory"); else asm volatile("s_waitcnt vmcnt(2)" ::: "memory"); } while (0)
; #define SLOAD(i, k0) do { st_[i].vs = *reinterpret_cast<const bf16x8*>(&Vh[(size_t)((k0) + sr) * LDK + sc]); \
;     st_[i].ks = *reinterpret_cast<const bf16x8*>(&Kh[(size_t)((k0) + sr) * LDK + sc]); \
;     if (DQ == 96) st_[i].kr = *reinterpret_cast<const bf16x8*>(&Kr[(size_t)((k0) + sr2) * 32 + sc2]); } while (0)
; #define SWRITE(b, i) do { *(bf16x8*)(V_lds + (b) * SHM_V + vst0) = st_[i].vs; *(bf16x8*)(K_lds + (b) * SHM_K + kst0) = st_[i].ks; \
;     if (DQ == 96) { if (tid < 256) *(bf16x8*)(K_lds + (b) * SHM_K + kst2) = st_[i].kr; } } while (0)
; #define SWAIT() do { if (DQ == 96) asm volatile("s_waitcnt vmcnt(3)" ::: "memory"); else asm volatile("s_waitcnt vmcnt(2)" ::: "memory"); } while (0)
; template <int DQ, bool WIN, int LDQ, int LDK> ...
;     ...
;     for (int j = 1; j + 1 < NT; j += 2) {
;         SBAR(); qkt<DQ>(pB0, pB1, K_lds + SHM_K, qr, minit, r32, hi);
;         finish(pA0, pA1); SBAR();
;         SLOAD(SO, KBASE(j + 2)); SBAR();
;         pv(vb0);
;         __syncthreads(); SWAIT(); SWRITE(0, SE);
;         lsum_upd();
;         if (WIN) win_mask(pB0, pB1, qrow - KBASE(j), hi);
;         exp16(pB0);
;         __syncthreads();
;         SBAR(); qkt<DQ>(pA0, pA1, K_lds, qr, minit, r32, hi);
;         finish(pB0, pB1); SBAR();
;         if (j + 3 < NT) SLOAD(SE, KBASE(j + 3)); SBAR();
.LBB0_493:
	s_add_i32 s21, s21, 2
	ds_read_b128 v[82:85], v156 offset:25600
	ds_read_b128 v[168:171], v156 offset:25632
	ds_read_b128 v[172:175], v156 offset:30208
	ds_read_b128 v[176:179], v156 offset:30240
	v_exp_f32_e32 v81, v81
	v_exp_f32_e32 v146, v66
	s_waitcnt lgkmcnt(3)
	v_mfma_f32_32x32x16_bf16 v[98:113], v[82:85], v[126:129], v[50:65]
	v_exp_f32_e32 v180, v67
	v_exp_f32_e32 v190, v68
	v_exp_f32_e32 v191, v73
	v_exp_f32_e32 v192, v74
	v_exp_f32_e32 v193, v75
	v_exp_f32_e32 v194, v80
	s_waitcnt lgkmcnt(1)
	v_mfma_f32_32x32x16_bf16 v[82:97], v[172:175], v[126:129], v[50:65]
	v_mfma_f32_32x32x16_bf16 v[98:113], v[168:171], v[122:125], v[98:113]
	ds_read_b128 v[168:171], v156 offset:25664
	ds_read_b128 v[172:175], v156 offset:25696
	ds_read_b128 v[182:185], v156 offset:30272
	ds_read_b128 v[186:189], v156 offset:30304
	v_cvt_pk_bf16_f32 v66, v138, v139
	v_cvt_pk_bf16_f32 v67, v162, v165
	v_cvt_pk_bf16_f32 v68, v163, v166
	s_waitcnt lgkmcnt(4)
	v_mfma_f32_32x32x16_bf16 v[82:97], v[176:179], v[122:125], v[82:97]
	v_exp_f32_e32 v176, v69
	v_exp_f32_e32 v177, v70
	v_exp_f32_e32 v178, v71
	v_exp_f32_e32 v179, v72
	v_cvt_pk_bf16_f32 v69, v164, v167
	v_cvt_pk_bf16_f32 v70, v140, v144
	v_cvt_pk_bf16_f32 v71, v141, v145
	s_waitcnt lgkmcnt(3)
	v_mfma_f32_32x32x16_bf16 v[98:113], v[168:171], v[118:121], v[98:113]
	v_exp_f32_e32 v168, v76
	v_exp_f32_e32 v169, v77
	v_exp_f32_e32 v170, v78
	v_exp_f32_e32 v171, v79
	v_cvt_pk_bf16_f32 v72, v142, v160
	v_cvt_pk_bf16_f32 v73, v143, v161
	v_cvt_pk_bf16_f32 v74, v146, v180
	s_waitcnt lgkmcnt(1)
	v_mfma_f32_32x32x16_bf16 v[82:97], v[182:185], v[118:121], v[82:97]
	v_cvt_pk_bf16_f32 v75, v190, v176
	v_cvt_pk_bf16_f32 v76, v177, v178
	v_cvt_pk_bf16_f32 v77, v179, v191
	v_cvt_pk_bf16_f32 v78, v192, v193
	v_cvt_pk_bf16_f32 v79, v168, v169
	v_cvt_pk_bf16_f32 v80, v170, v171
	v_cvt_pk_bf16_f32 v81, v194, v81
	v_mfma_f32_32x32x16_bf16 v[98:113], v[172:175], v[114:117], v[98:113]
	s_waitcnt lgkmcnt(0)
	v_mfma_f32_32x32x16_bf16 v[82:97], v[186:189], v[114:117], v[82:97]
	v_add_co_u32_e32 v142, vcc, s90, v148
	s_nop 1
	v_addc_co_u32_e32 v143, vcc, -1, v149, vcc
	global_load_dwordx4 v[138:141], v[142:143], off
	s_nop 0
	global_load_dwordx4 v[142:145], v[142:143], off offset:-256
	ds_read_b64_tr_b16 v[160:161], v159 offset:0
	ds_read_b64_tr_b16 v[162:163], v159 offset:0x400
	ds_read_b64_tr_b16 v[164:165], v159 offset:0x800
	ds_read_b64_tr_b16 v[166:167], v159 offset:0xc00
	ds_read_b64_tr_b16 v[168:169], v159 offset:0x1000
	ds_read_b64_tr_b16 v[170:171], v159 offset:0x1400
	ds_read_b64_tr_b16 v[172:173], v159 offset:0x1800
	ds_read_b64_tr_b16 v[174:175], v159 offset:0x1c00
	s_waitcnt lgkmcnt(0)
	s_nop 0
	v_mfma_f32_32x32x16_bf16 v[2:17], v[66:69], v[160:163], v[2:17]
	ds_read_b64_tr_b16 v[160:161], v159 offset:0x200
	ds_read_b64_tr_b16 v[162:163], v159 offset:0x600
	v_mfma_f32_32x32x16_bf16 v[2:17], v[70:73], v[164:167], v[2:17]
	ds_read_b64_tr_b16 v[164:165], v159 offset:0xa00
	ds_read_b64_tr_b16 v[166:167], v159 offset:0xe00
	v_mfma_f32_32x32x16_bf16 v[2:17], v[74:77], v[168:171], v[2:17]
	ds_read_b64_tr_b16 v[168:169], v159 offset:0x1200
	ds_read_b64_tr_b16 v[170:171], v159 offset:0x1600
	ds_read_b64_tr_b16 v[176:177], v159 offset:0x1a00
	ds_read_b64_tr_b16 v[178:179], v159 offset:0x1e00
	s_waitcnt lgkmcnt(0)
	v_mfma_f32_32x32x16_bf16 v[2:17], v[78:81], v[172:175], v[2:17]
	v_mfma_f32_32x32x16_bf16 v[18:33], v[66:69], v[160:163], v[18:33]
	v_mov_b64_e32 v[162:163], s[14:15]
	v_mov_b64_e32 v[160:161], s[12:13]
	s_waitcnt vmcnt(2)
	s_waitcnt vmcnt(2)
	ds_write_b128 v158, v[134:137]
	ds_write_b128 v157, v[130:133] offset:16384
	v_mfma_f32_32x32x16_bf16 v[34:49], v[66:69], v[160:163], v[34:49]
	v_exp_f32_e32 v146, v98
	v_exp_f32_e32 v180, v99
	v_exp_f32_e32 v182, v100
	v_exp_f32_e32 v183, v101
	v_exp_f32_e32 v184, v102
	v_exp_f32_e32 v185, v103
	v_exp_f32_e32 v186, v104
	v_mfma_f32_32x32x16_bf16 v[18:33], v[70:73], v[164:167], v[18:33]
	v_exp_f32_e32 v187, v105
	v_exp_f32_e32 v188, v106
	v_exp_f32_e32 v189, v107
	v_exp_f32_e32 v190, v108
	v_exp_f32_e32 v191, v109
	v_exp_f32_e32 v192, v110
	v_exp_f32_e32 v193, v111
	v_mfma_f32_32x32x16_bf16 v[34:49], v[70:73], v[160:163], v[34:49]
	v_exp_f32_e32 v194, v112
	v_exp_f32_e32 v195, v113
	s_waitcnt lgkmcnt(0)
	s_barrier
	v_mfma_f32_32x32x16_bf16 v[18:33], v[74:77], v[168:171], v[18:33]
	v_mfma_f32_32x32x16_bf16 v[34:49], v[74:77], v[160:163], v[34:49]
	v_mfma_f32_32x32x16_bf16 v[18:33], v[78:81], v[176:179], v[18:33]
	v_mfma_f32_32x32x16_bf16 v[34:49], v[78:81], v[160:163], v[34:49]
	ds_read_b128 v[66:69], v156 offset:16384
	ds_read_b128 v[160:163], v156 offset:16416
	ds_read_b128 v[164:167], v156 offset:20992
	ds_read_b128 v[168:171], v156 offset:21024
	v_exp_f32_e32 v82, v82
	v_exp_f32_e32 v83, v83
	s_waitcnt lgkmcnt(3)
	v_mfma_f32_32x32x16_bf16 v[98:113], v[66:69], v[126:129], v[50:65]
	v_exp_f32_e32 v84, v84
	v_exp_f32_e32 v85, v85
	v_exp_f32_e32 v89, v89
	v_exp_f32_e32 v196, v91
	v_exp_f32_e32 v197, v96
	v_exp_f32_e32 v198, v97
	s_waitcnt lgkmcnt(1)
	v_mfma_f32_32x32x16_bf16 v[66:81], v[164:167], v[126:129], v[50:65]
	v_mfma_f32_32x32x16_bf16 v[98:113], v[160:163], v[122:125], v[98:113]
	ds_read_b128 v[160:163], v156 offset:16448
	ds_read_b128 v[164:167], v156 offset:16480
	ds_read_b128 v[172:175], v156 offset:21056
	ds_read_b128 v[176:179], v156 offset:21088
	s_waitcnt lgkmcnt(4)
	v_mfma_f32_32x32x16_bf16 v[66:81], v[168:171], v[122:125], v[66:81]
	v_exp_f32_e32 v168, v86
	v_exp_f32_e32 v169, v87
	v_exp_f32_e32 v170, v88
	v_exp_f32_e32 v171, v90
	s_waitcnt lgkmcnt(3)
	v_mfma_f32_32x32x16_bf16 v[98:113], v[160:163], v[118:121], v[98:113]
	v_exp_f32_e32 v160, v92
	v_exp_f32_e32 v161, v93
	v_exp_f32_e32 v162, v94
	v_exp_f32_e32 v163, v95
	v_cvt_pk_bf16_f32 v94, v146, v180
	v_cvt_pk_bf16_f32 v95, v182, v183
	v_cvt_pk_bf16_f32 v96, v184, v185
	s_waitcnt lgkmcnt(1)
	v_mfma_f32_32x32x16_bf16 v[66:81], v[172:175], v[118:121], v[66:81]
	v_cvt_pk_bf16_f32 v97, v186, v187
	v_cvt_pk_bf16_f32 v90, v188, v189
	v_cvt_pk_bf16_f32 v91, v190, v191
	v_cvt_pk_bf16_f32 v92, v192, v193
	v_cvt_pk_bf16_f32 v93, v194, v195
	v_cvt_pk_bf16_f32 v86, v82, v83
	v_cvt_pk_bf16_f32 v87, v84, v85
	v_mfma_f32_32x32x16_bf16 v[98:113], v[164:167], v[114:117], v[98:113]
	v_cvt_pk_bf16_f32 v88, v168, v169
	v_cvt_pk_bf16_f32 v89, v170, v89
	v_cvt_pk_bf16_f32 v82, v171, v196
	v_cvt_pk_bf16_f32 v83, v160, v161
	v_cvt_pk_bf16_f32 v84, v162, v163
	v_cvt_pk_bf16_f32 v85, v197, v198
	s_waitcnt lgkmcnt(0)
	v_mfma_f32_32x32x16_bf16 v[66:81], v[176:179], v[114:117], v[66:81]
	s_cmpk_gt_u32 s21, 0x7c
	s_cselect_b64 s[0:1], -1, 0
	s_and_b64 vcc, exec, s[0:1]
	s_cbranch_vccnz .LBB0_492
	global_load_dwordx4 v[134:137], v[148:149], off
	global_load_dwordx4 v[130:133], v[148:149], off offset:-256
	s_branch .LBB0_492
